# GEMM mainloop: removed the compiler's duplicate s_waitcnt lgkmcnt(0) at the head of each MFMA segment (12 sites incl. peeled iteration)
# speedup vs baseline: 1.0087x; 1.0039x over previous
; #define PG8_STAGE(bufoff, gbase, voff) do { _Pragma("unroll") for (int _i = 0; _i < 2; ++_i) \
;         __builtin_amdgcn_global_load_lds((const unsigned*)((const char*)(gbase) + (voff)[_i]), (LAS unsigned*)(lds + (bufoff) + ldsw + _i * 8192), 16, 0, 0); } while (0)
; #define PG8_LDA(dst, b, h) do { _Pragma("unroll") for (int m = 0; m < 4; ++m) _Pragma("unroll") for (int k = 0; k < 2; ++k) dst[m][k] = *(const LAS bf16x8*)(lds + PG8_SA(b, h) + aoff + m * 2048 + k * 1024); } while (0)
; #define PG8_WAIT_V(n) asm volatile("s_waitcnt vmcnt(" #n ")" ::: "memory")
; #define PG8_WAIT_L(n) asm volatile("s_waitcnt lgkmcnt(" #n ")" ::: "memory")
; template <class Epi>
; DI void gemm_phase(LAS unsigned char* lds, const Gemm g, const StaticOrder& S, const Epi& E, const int tid) {
;     ...
;         for (int t = 0; t < nt; t += 2) {
;             const bool last = (t == nt - 2);
;             const char* a1 = cA + (size_t)(t + 1) * kstep;
;             const char* a2 = last ? nA : cA + (size_t)(t + 2) * kstep; const char* b2 = last ? nB : cB + (size_t)(t + 2) * kstep;
;             const char* a3 = a2 + kstep; const char* b3 = b2 + kstep;
;             PG8_LDB(B0, 0, 0); PG8_SCHED; PG8_LDA(At, 0, 0); PG8_STAGE(PG8_SA(1, 1), a1 + hstep, voffA);
;             PG8_WAIT_L(8); PG8_BAR; PG8_WAIT_L(0); PG8_MMA(0, 0, At, B0); PG8_BAR; PG8_SCHED;
;             PG8_LDB(B1, 0, 1); PG8_STAGE(PG8_SB(0, 0), b2, voffB);
;             PG8_BAR; PG8_WAIT_L(0); PG8_MMA(0, 1, At, B1); PG8_BAR;
;             PG8_LDA(At, 0, 1); PG8_STAGE(PG8_SA(0, 0), a2, voffA);
;             PG8_BAR; PG8_WAIT_L(0); PG8_MMA(1, 0, At, B0); PG8_BAR; PG8_SCHED;
;             PG8_STAGE(PG8_SB(0, 1), b2 + hstep, voffB);
;             PG8_WAIT_V(6); PG8_BAR; PG8_MMA(1, 1, At, B1); PG8_BAR;
;             PG8_LDB(B0, 1, 0); PG8_SCHED; PG8_LDA(At, 1, 0); PG8_STAGE(PG8_SA(0, 1), a2 + hstep, voffA);
;             PG8_WAIT_L(8); PG8_BAR; PG8_WAIT_L(0); PG8_MMA(0, 0, At, B0); PG8_BAR; PG8_SCHED;
;             PG8_LDB(B1, 1, 1); PG8_STAGE(PG8_SB(1, 0), b3, voffB);
;             PG8_BAR; PG8_WAIT_L(0); PG8_MMA(0, 1, At, B1); PG8_BAR;
;             PG8_LDA(At, 1, 1); PG8_STAGE(PG8_SA(1, 0), a3, voffA);
;             PG8_BAR; PG8_WAIT_L(0); PG8_MMA(1, 0, At, B0); PG8_BAR; PG8_SCHED;
;             PG8_STAGE(PG8_SB(1, 1), b3 + hstep, voffB);
;             PG8_WAIT_V(6); PG8_BAR; PG8_MMA(1, 1, At, B1); PG8_BAR;
.LBB0_742:
	s_add_u32 s20, s20, 0x80
	s_addc_u32 s21, s21, 0
	s_add_u32 s81, s18, 0x100
	s_addc_u32 s82, s19, 0
	s_mov_b32 s18, 0
	ds_read_b128 v[138:141], v212
	ds_read_b128 v[150:153], v212 offset:1024
	ds_read_b128 v[154:157], v212 offset:2048
	ds_read_b128 v[158:161], v212 offset:3072
	s_add_i32 s83, s18, 2
	s_add_u32 s22, s20, 0x80
	s_addc_u32 s19, s21, 0
	s_cmp_eq_u32 s60, s18
	s_cselect_b32 s18, s8, s22
	s_cselect_b32 s19, s9, s19
	s_cselect_b32 s23, s17, s82
	s_cselect_b32 s22, s16, s81
	s_add_i32 m0, s49, 0xc000
	ds_read_b128 v[162:165], v148
	ds_read_b128 v[166:169], v148 offset:1024
	ds_read_b128 v[170:173], v148 offset:2048
	ds_read_b128 v[174:177], v148 offset:3072
	ds_read_b128 v[178:181], v148 offset:4096
	ds_read_b128 v[182:185], v148 offset:5120
	ds_read_b128 v[186:189], v148 offset:6144
	ds_read_b128 v[190:193], v148 offset:7168
	global_load_lds_dwordx4 v134, s[20:21]
	s_add_i32 m0, s49, 0xe000
	s_nop 0
	global_load_lds_dwordx4 v136, s[20:21]
	s_waitcnt lgkmcnt(8)
	s_barrier
	s_waitcnt lgkmcnt(0)
	s_setprio 1
	v_mfma_f32_16x16x32_bf16 v[24:27], v[138:141], v[162:165], 0
	v_mfma_f32_16x16x32_bf16 v[28:31], v[154:157], v[162:165], 0
	v_mfma_f32_16x16x32_bf16 v[16:19], v[138:141], v[170:173], 0
	v_mfma_f32_16x16x32_bf16 v[20:23], v[154:157], v[170:173], 0
	v_mfma_f32_16x16x32_bf16 v[8:11], v[138:141], v[178:181], 0
	v_mfma_f32_16x16x32_bf16 v[12:15], v[154:157], v[178:181], 0
	v_mfma_f32_16x16x32_bf16 v[0:3], v[138:141], v[186:189], 0
	v_mfma_f32_16x16x32_bf16 v[4:7], v[154:157], v[186:189], 0
	v_mfma_f32_16x16x32_bf16 v[24:27], v[150:153], v[166:169], v[24:27]
	v_mfma_f32_16x16x32_bf16 v[28:31], v[158:161], v[166:169], v[28:31]
	v_mfma_f32_16x16x32_bf16 v[16:19], v[150:153], v[174:177], v[16:19]
	v_mfma_f32_16x16x32_bf16 v[20:23], v[158:161], v[174:177], v[20:23]
	v_mfma_f32_16x16x32_bf16 v[8:11], v[150:153], v[182:185], v[8:11]
	v_mfma_f32_16x16x32_bf16 v[12:15], v[158:161], v[182:185], v[12:15]
	v_mfma_f32_16x16x32_bf16 v[0:3], v[150:153], v[190:193], v[0:3]
	v_mfma_f32_16x16x32_bf16 v[4:7], v[158:161], v[190:193], v[4:7]
	s_setprio 0
	s_barrier
	s_add_i32 s89, 0, 0x14000
	s_add_i32 vcc_lo, s26, s4
	s_mov_b32 m0, vcc_lo
	ds_read_b128 v[194:197], v213
	ds_read_b128 v[200:203], v213 offset:1024
	ds_read_b128 v[204:207], v213 offset:2048
	ds_read_b128 v[208:211], v213 offset:3072
	global_load_lds_dwordx4 v198, s[22:23]
	s_add_i32 m0, vcc_lo, 0x2000
	s_nop 0
	global_load_lds_dwordx4 v128, s[22:23]
	s_barrier
	s_waitcnt lgkmcnt(0)
	s_setprio 1
	v_mfma_f32_16x16x32_bf16 v[88:91], v[194:197], v[162:165], 0
	v_mfma_f32_16x16x32_bf16 v[96:99], v[204:207], v[162:165], 0
	v_mfma_f32_16x16x32_bf16 v[80:83], v[194:197], v[170:173], 0
	v_mfma_f32_16x16x32_bf16 v[84:87], v[204:207], v[170:173], 0
	v_mfma_f32_16x16x32_bf16 v[72:75], v[194:197], v[178:181], 0
	v_mfma_f32_16x16x32_bf16 v[76:79], v[204:207], v[178:181], 0
	v_mfma_f32_16x16x32_bf16 v[56:59], v[194:197], v[186:189], 0
	v_mfma_f32_16x16x32_bf16 v[64:67], v[204:207], v[186:189], 0
	v_mfma_f32_16x16x32_bf16 v[88:91], v[200:203], v[166:169], v[88:91]
	v_mfma_f32_16x16x32_bf16 v[96:99], v[208:211], v[166:169], v[96:99]
	v_mfma_f32_16x16x32_bf16 v[80:83], v[200:203], v[174:177], v[80:83]
	v_mfma_f32_16x16x32_bf16 v[84:87], v[208:211], v[174:177], v[84:87]
	v_mfma_f32_16x16x32_bf16 v[72:75], v[200:203], v[182:185], v[72:75]
	v_mfma_f32_16x16x32_bf16 v[76:79], v[208:211], v[182:185], v[76:79]
	v_mfma_f32_16x16x32_bf16 v[56:59], v[200:203], v[190:193], v[56:59]
	v_mfma_f32_16x16x32_bf16 v[64:67], v[208:211], v[190:193], v[64:67]
	s_setprio 0
	s_mov_b32 m0, s49
	s_barrier
	ds_read_b128 v[162:165], v148 offset:16384
	ds_read_b128 v[166:169], v148 offset:17408
	ds_read_b128 v[170:173], v148 offset:18432
	ds_read_b128 v[174:177], v148 offset:19456
	ds_read_b128 v[178:181], v148 offset:20480
	ds_read_b128 v[182:185], v148 offset:21504
	ds_read_b128 v[186:189], v148 offset:22528
	ds_read_b128 v[190:193], v148 offset:23552
	global_load_lds_dwordx4 v132, s[18:19]
	s_mov_b32 m0, s52
	s_nop 0
	global_load_lds_dwordx4 v130, s[18:19]
	s_barrier
	s_waitcnt lgkmcnt(0)
	s_setprio 1
	v_mfma_f32_16x16x32_bf16 v[60:63], v[138:141], v[162:165], 0
	v_mfma_f32_16x16x32_bf16 v[68:71], v[154:157], v[162:165], 0
	v_mfma_f32_16x16x32_bf16 v[48:51], v[138:141], v[170:173], 0
	v_mfma_f32_16x16x32_bf16 v[52:55], v[154:157], v[170:173], 0
	v_mfma_f32_16x16x32_bf16 v[40:43], v[138:141], v[178:181], 0
	v_mfma_f32_16x16x32_bf16 v[44:47], v[154:157], v[178:181], 0
	v_mfma_f32_16x16x32_bf16 v[32:35], v[138:141], v[186:189], 0
	v_mfma_f32_16x16x32_bf16 v[36:39], v[154:157], v[186:189], 0
	v_mfma_f32_16x16x32_bf16 v[60:63], v[150:153], v[166:169], v[60:63]
	v_mfma_f32_16x16x32_bf16 v[68:71], v[158:161], v[166:169], v[68:71]
	v_mfma_f32_16x16x32_bf16 v[48:51], v[150:153], v[174:177], v[48:51]
	v_mfma_f32_16x16x32_bf16 v[52:55], v[158:161], v[174:177], v[52:55]
	v_mfma_f32_16x16x32_bf16 v[40:43], v[150:153], v[182:185], v[40:43]
	v_mfma_f32_16x16x32_bf16 v[44:47], v[158:161], v[182:185], v[44:47]
	v_mfma_f32_16x16x32_bf16 v[32:35], v[150:153], v[190:193], v[32:35]
	v_mfma_f32_16x16x32_bf16 v[36:39], v[158:161], v[190:193], v[36:39]
	s_setprio 0
	s_barrier
	s_add_u32 s22, s22, s84
	s_addc_u32 s23, s23, 0
	s_add_i32 s89, s89, s4
	s_mov_b32 m0, s89
	s_nop 0
	global_load_lds_dwordx4 v198, s[22:23]
	s_add_i32 m0, s89, 0x2000
	s_nop 0
	global_load_lds_dwordx4 v128, s[22:23]
	s_waitcnt vmcnt(6)
	s_barrier
; #define PG8_STAGE(bufoff, gbase, voff) do { _Pragma("unroll") for (int _i = 0; _i < 2; ++_i) \
;         __builtin_amdgcn_global_load_lds((const unsigned*)((const char*)(gbase) + (voff)[_i]), (LAS unsigned*)(lds + (bufoff) + ldsw + _i * 8192), 16, 0, 0); } while (0)
; #define PG8_LDA(dst, b, h) do { _Pragma("unroll") for (int m = 0; m < 4; ++m) _Pragma("unroll") for (int k = 0; k < 2; ++k) dst[m][k] = *(const LAS bf16x8*)(lds + PG8_SA(b, h) + aoff + m * 2048 + k * 1024); } while (0)
; #define PG8_LDB(dst, b, h) do { _Pragma("unroll") for (int n = 0; n < 2; ++n) _Pragma("unroll") for (int k = 0; k < 2; ++k) dst[n][k] = *(const LAS bf16x8*)(lds + PG8_SB(b, h) + boff + n * 2048 + k * 1024); } while (0)
; #define PG8_MMA(ai, bj, At, Bt) do { __builtin_amdgcn_s_setprio(1); _Pragma("unroll") for (int m = 0; m < 4; ++m) _Pragma("unroll") for (int n = 0; n < 2; ++n) _Pragma("unroll") for (int k = 0; k < 2; ++k) \
;         acc[ai][bj][m][n] = __builtin_amdgcn_mfma_f32_16x16x32_bf16(Bt[n][k], At[m][k], acc[ai][bj][m][n], 0, 0, 0); __builtin_amdgcn_s_setprio(0); } while (0)
; #define PG8_WAIT_V(n) asm volatile("s_waitcnt vmcnt(" #n ")" ::: "memory")
; #define PG8_WAIT_L(n) asm volatile("s_waitcnt lgkmcnt(" #n ")" ::: "memory")
; #define PG8_BAR __builtin_amdgcn_s_barrier()
; #define PG8_SCHED __builtin_amdgcn_sched_barrier(0)
; template <class Epi>
; DI void gemm_phase(LAS unsigned char* lds, const Gemm g, const StaticOrder& S, const Epi& E, const int tid) {
;     ...
;             PG8_WAIT_V(6); PG8_BAR; PG8_MMA(1, 1, At, B1); PG8_BAR;
;             PG8_LDB(B0, 1, 0); PG8_SCHED; PG8_LDA(At, 1, 0); PG8_STAGE(PG8_SA(0, 1), a2 + hstep, voffA);
;             PG8_WAIT_L(8); PG8_BAR; PG8_WAIT_L(0); PG8_MMA(0, 0, At, B0); PG8_BAR; PG8_SCHED;
;             PG8_LDB(B1, 1, 1); PG8_STAGE(PG8_SB(1, 0), b3, voffB);
;             PG8_BAR; PG8_WAIT_L(0); PG8_MMA(0, 1, At, B1); PG8_BAR;
;             PG8_LDA(At, 1, 1); PG8_STAGE(PG8_SA(1, 0), a3, voffA);
;             PG8_BAR; PG8_WAIT_L(0); PG8_MMA(1, 0, At, B0); PG8_BAR; PG8_SCHED;
;             PG8_STAGE(PG8_SB(1, 1), b3 + hstep, voffB);
;             PG8_WAIT_V(6); PG8_BAR; PG8_MMA(1, 1, At, B1); PG8_BAR;
	s_setprio 1
	v_mfma_f32_16x16x32_bf16 v[120:123], v[194:197], v[162:165], 0
	v_mfma_f32_16x16x32_bf16 v[124:127], v[204:207], v[162:165], 0
	v_mfma_f32_16x16x32_bf16 v[112:115], v[194:197], v[170:173], 0
	v_mfma_f32_16x16x32_bf16 v[116:119], v[204:207], v[170:173], 0
	v_mfma_f32_16x16x32_bf16 v[104:107], v[194:197], v[178:181], 0
	v_mfma_f32_16x16x32_bf16 v[108:111], v[204:207], v[178:181], 0
	v_mfma_f32_16x16x32_bf16 v[92:95], v[194:197], v[186:189], 0
	v_mfma_f32_16x16x32_bf16 v[100:103], v[204:207], v[186:189], 0
	v_mfma_f32_16x16x32_bf16 v[120:123], v[200:203], v[166:169], v[120:123]
	v_mfma_f32_16x16x32_bf16 v[124:127], v[208:211], v[166:169], v[124:127]
	v_mfma_f32_16x16x32_bf16 v[112:115], v[200:203], v[174:177], v[112:115]
	v_mfma_f32_16x16x32_bf16 v[116:119], v[208:211], v[174:177], v[116:119]
	v_mfma_f32_16x16x32_bf16 v[104:107], v[200:203], v[182:185], v[104:107]
	v_mfma_f32_16x16x32_bf16 v[108:111], v[208:211], v[182:185], v[108:111]
	v_mfma_f32_16x16x32_bf16 v[92:95], v[200:203], v[190:193], v[92:95]
	v_mfma_f32_16x16x32_bf16 v[100:103], v[208:211], v[190:193], v[100:103]
	s_setprio 0
	s_add_i32 s22, 0, 0x18000
	s_barrier
	ds_read_b128 v[138:141], v214
	ds_read_b128 v[150:153], v214 offset:1024
	ds_read_b128 v[154:157], v214 offset:2048
	ds_read_b128 v[158:161], v214 offset:3072
	s_add_u32 s18, s18, s84
	s_addc_u32 s19, s19, 0
	s_mov_b32 m0, s53
	ds_read_b128 v[162:165], v148 offset:32768
	ds_read_b128 v[166:169], v148 offset:33792
	ds_read_b128 v[170:173], v148 offset:34816
	ds_read_b128 v[174:177], v148 offset:35840
	ds_read_b128 v[178:181], v148 offset:36864
	ds_read_b128 v[182:185], v148 offset:37888
	ds_read_b128 v[186:189], v148 offset:38912
	ds_read_b128 v[190:193], v148 offset:39936
	global_load_lds_dwordx4 v132, s[18:19]
	s_mov_b32 m0, s54
	s_nop 0
	global_load_lds_dwordx4 v130, s[18:19]
	s_waitcnt lgkmcnt(8)
	s_barrier
	s_waitcnt lgkmcnt(0)
	s_setprio 1
	v_mfma_f32_16x16x32_bf16 v[24:27], v[138:141], v[162:165], v[24:27]
	v_mfma_f32_16x16x32_bf16 v[28:31], v[154:157], v[162:165], v[28:31]
	v_mfma_f32_16x16x32_bf16 v[16:19], v[138:141], v[170:173], v[16:19]
	v_mfma_f32_16x16x32_bf16 v[20:23], v[154:157], v[170:173], v[20:23]
	v_mfma_f32_16x16x32_bf16 v[8:11], v[138:141], v[178:181], v[8:11]
	v_mfma_f32_16x16x32_bf16 v[12:15], v[154:157], v[178:181], v[12:15]
	v_mfma_f32_16x16x32_bf16 v[0:3], v[138:141], v[186:189], v[0:3]
	v_mfma_f32_16x16x32_bf16 v[4:7], v[154:157], v[186:189], v[4:7]
	v_mfma_f32_16x16x32_bf16 v[24:27], v[150:153], v[166:169], v[24:27]
	v_mfma_f32_16x16x32_bf16 v[28:31], v[158:161], v[166:169], v[28:31]
	v_mfma_f32_16x16x32_bf16 v[16:19], v[150:153], v[174:177], v[16:19]
	v_mfma_f32_16x16x32_bf16 v[20:23], v[158:161], v[174:177], v[20:23]
	v_mfma_f32_16x16x32_bf16 v[8:11], v[150:153], v[182:185], v[8:11]
	v_mfma_f32_16x16x32_bf16 v[12:15], v[158:161], v[182:185], v[12:15]
	v_mfma_f32_16x16x32_bf16 v[0:3], v[150:153], v[190:193], v[0:3]
	v_mfma_f32_16x16x32_bf16 v[4:7], v[158:161], v[190:193], v[4:7]
	s_setprio 0
	s_barrier
	s_add_i32 s18, 0, 0x1c000
	s_add_i32 s19, s22, s4
	s_mov_b32 m0, s19
	ds_read_b128 v[194:197], v215
	ds_read_b128 v[200:203], v215 offset:1024
	ds_read_b128 v[204:207], v215 offset:2048
	ds_read_b128 v[208:211], v215 offset:3072
	s_add_i32 vcc_hi, s60, 2
	s_cmp_eq_u32 vcc_hi, s83
	s_cselect_b32 s100, s16, s81
	s_cselect_b32 s101, s17, s82
	s_add_u32 s100, s100, 0x80
	s_addc_u32 s101, s101, 0
	global_load_lds_dwordx4 v198, s[100:101]
	s_add_i32 m0, s19, 0x2000
	s_nop 0
	global_load_lds_dwordx4 v128, s[100:101]
	s_barrier
	s_waitcnt lgkmcnt(0)
	s_setprio 1
	v_mfma_f32_16x16x32_bf16 v[88:91], v[194:197], v[162:165], v[88:91]
	v_mfma_f32_16x16x32_bf16 v[96:99], v[204:207], v[162:165], v[96:99]
	v_mfma_f32_16x16x32_bf16 v[80:83], v[194:197], v[170:173], v[80:83]
	v_mfma_f32_16x16x32_bf16 v[84:87], v[204:207], v[170:173], v[84:87]
	v_mfma_f32_16x16x32_bf16 v[72:75], v[194:197], v[178:181], v[72:75]
	v_mfma_f32_16x16x32_bf16 v[76:79], v[204:207], v[178:181], v[76:79]
	v_mfma_f32_16x16x32_bf16 v[56:59], v[194:197], v[186:189], v[56:59]
	v_mfma_f32_16x16x32_bf16 v[64:67], v[204:207], v[186:189], v[64:67]
	v_mfma_f32_16x16x32_bf16 v[88:91], v[200:203], v[166:169], v[88:91]
	v_mfma_f32_16x16x32_bf16 v[96:99], v[208:211], v[166:169], v[96:99]
	v_mfma_f32_16x16x32_bf16 v[80:83], v[200:203], v[174:177], v[80:83]
	v_mfma_f32_16x16x32_bf16 v[84:87], v[208:211], v[174:177], v[84:87]
	v_mfma_f32_16x16x32_bf16 v[72:75], v[200:203], v[182:185], v[72:75]
	v_mfma_f32_16x16x32_bf16 v[76:79], v[208:211], v[182:185], v[76:79]
	v_mfma_f32_16x16x32_bf16 v[56:59], v[200:203], v[190:193], v[56:59]
	v_mfma_f32_16x16x32_bf16 v[64:67], v[208:211], v[190:193], v[64:67]
	s_setprio 0
	s_mov_b32 m0, s55
	s_barrier
	ds_read_b128 v[162:165], v148 offset:49152
	ds_read_b128 v[166:169], v148 offset:50176
	ds_read_b128 v[170:173], v148 offset:51200
	ds_read_b128 v[174:177], v148 offset:52224
	ds_read_b128 v[178:181], v148 offset:53248
	ds_read_b128 v[182:185], v148 offset:54272
	ds_read_b128 v[186:189], v148 offset:55296
	ds_read_b128 v[190:193], v148 offset:56320
	s_add_u32 s100, s20, 0x80
	s_addc_u32 s101, s21, 0
	s_add_i32 vcc_hi, s60, 2
	s_cmp_eq_u32 vcc_hi, s83
	s_cselect_b32 s100, s8, s100
	s_cselect_b32 s101, s9, s101
	s_add_u32 s100, s100, 0x80
	s_addc_u32 s101, s101, 0
	global_load_lds_dwordx4 v132, s[100:101]
	s_mov_b32 m0, s56
	s_nop 0
	global_load_lds_dwordx4 v130, s[100:101]
	s_barrier
; #define PG8_STAGE(bufoff, gbase, voff) do { _Pragma("unroll") for (int _i = 0; _i < 2; ++_i) \
;         __builtin_amdgcn_global_load_lds((const unsigned*)((const char*)(gbase) + (voff)[_i]), (LAS unsigned*)(lds + (bufoff) + ldsw + _i * 8192), 16, 0, 0); } while (0)
; #define PG8_LDA(dst, b, h) do { _Pragma("unroll") for (int m = 0; m < 4; ++m) _Pragma("unroll") for (int k = 0; k < 2; ++k) dst[m][k] = *(const LAS bf16x8*)(lds + PG8_SA(b, h) + aoff + m * 2048 + k * 1024); } while (0)
; #define PG8_LDB(dst, b, h) do { _Pragma("unroll") for (int n = 0; n < 2; ++n) _Pragma("unroll") for (int k = 0; k < 2; ++k) dst[n][k] = *(const LAS bf16x8*)(lds + PG8_SB(b, h) + boff + n * 2048 + k * 1024); } while (0)
; #define PG8_MMA(ai, bj, At, Bt) do { __builtin_amdgcn_s_setprio(1); _Pragma("unroll") for (int m = 0; m < 4; ++m) _Pragma("unroll") for (int n = 0; n < 2; ++n) _Pragma("unroll") for (int k = 0; k < 2; ++k) \
;         acc[ai][bj][m][n] = __builtin_amdgcn_mfma_f32_16x16x32_bf16(Bt[n][k], At[m][k], acc[ai][bj][m][n], 0, 0, 0); __builtin_amdgcn_s_setprio(0); } while (0)
; #define PG8_WAIT_V(n) asm volatile("s_waitcnt vmcnt(" #n ")" ::: "memory")
; #define PG8_WAIT_L(n) asm volatile("s_waitcnt lgkmcnt(" #n ")" ::: "memory")
; #define PG8_BAR __builtin_amdgcn_s_barrier()
; #define PG8_SCHED __builtin_amdgcn_sched_barrier(0)
; template <class Epi>
; DI void gemm_phase(LAS unsigned char* lds, const Gemm g, const StaticOrder& S, const Epi& E, const int tid) {
;     ...
;             PG8_LDB(B0, 0, 0); PG8_SCHED; PG8_LDA(At, 0, 0); PG8_STAGE(PG8_SA(1, 1), a1 + hstep, voffA);
;             PG8_WAIT_L(8); PG8_BAR; PG8_WAIT_L(0); PG8_MMA(0, 0, At, B0); PG8_BAR; PG8_SCHED;
;             PG8_LDB(B1, 0, 1); PG8_STAGE(PG8_SB(0, 0), b2, voffB);
;             PG8_BAR; PG8_WAIT_L(0); PG8_MMA(0, 1, At, B1); PG8_BAR;
;     ...
;             PG8_BAR; PG8_WAIT_L(0); PG8_MMA(0, 1, At, B1); PG8_BAR;
;             PG8_LDA(At, 1, 1); PG8_STAGE(PG8_SA(1, 0), a3, voffA);
;             PG8_BAR; PG8_WAIT_L(0); PG8_MMA(1, 0, At, B0); PG8_BAR; PG8_SCHED;
;             PG8_STAGE(PG8_SB(1, 1), b3 + hstep, voffB);
;             PG8_WAIT_V(6); PG8_BAR; PG8_MMA(1, 1, At, B1); PG8_BAR;
	s_waitcnt lgkmcnt(0)
	s_setprio 1
	v_mfma_f32_16x16x32_bf16 v[60:63], v[138:141], v[162:165], v[60:63]
	v_mfma_f32_16x16x32_bf16 v[68:71], v[154:157], v[162:165], v[68:71]
	v_mfma_f32_16x16x32_bf16 v[48:51], v[138:141], v[170:173], v[48:51]
	v_mfma_f32_16x16x32_bf16 v[52:55], v[154:157], v[170:173], v[52:55]
	v_mfma_f32_16x16x32_bf16 v[40:43], v[138:141], v[178:181], v[40:43]
	v_mfma_f32_16x16x32_bf16 v[44:47], v[154:157], v[178:181], v[44:47]
	v_mfma_f32_16x16x32_bf16 v[32:35], v[138:141], v[186:189], v[32:35]
	v_mfma_f32_16x16x32_bf16 v[36:39], v[154:157], v[186:189], v[36:39]
	v_mfma_f32_16x16x32_bf16 v[60:63], v[150:153], v[166:169], v[60:63]
	v_mfma_f32_16x16x32_bf16 v[68:71], v[158:161], v[166:169], v[68:71]
	v_mfma_f32_16x16x32_bf16 v[48:51], v[150:153], v[174:177], v[48:51]
	v_mfma_f32_16x16x32_bf16 v[52:55], v[158:161], v[174:177], v[52:55]
	v_mfma_f32_16x16x32_bf16 v[40:43], v[150:153], v[182:185], v[40:43]
	v_mfma_f32_16x16x32_bf16 v[44:47], v[158:161], v[182:185], v[44:47]
	v_mfma_f32_16x16x32_bf16 v[32:35], v[150:153], v[190:193], v[32:35]
	v_mfma_f32_16x16x32_bf16 v[36:39], v[158:161], v[190:193], v[36:39]
	s_setprio 0
	s_barrier
	s_add_i32 s18, s18, s4
	s_add_i32 vcc_hi, s60, 2
	s_cmp_eq_u32 vcc_hi, s83
	s_cselect_b32 s100, s16, s81
	s_cselect_b32 s101, s17, s82
	s_add_u32 s100, s100, s84
	s_addc_u32 s101, s101, 0
	s_add_u32 s100, s100, 0x80
	s_addc_u32 s101, s101, 0
	s_mov_b32 m0, s18
	s_nop 0
	global_load_lds_dwordx4 v198, s[100:101]
	s_add_i32 m0, s18, 0x2000
	s_nop 0
	global_load_lds_dwordx4 v128, s[100:101]
	s_waitcnt vmcnt(6)
	s_barrier
	s_setprio 1
	v_mfma_f32_16x16x32_bf16 v[120:123], v[194:197], v[162:165], v[120:123]
	v_mfma_f32_16x16x32_bf16 v[124:127], v[204:207], v[162:165], v[124:127]
	v_mfma_f32_16x16x32_bf16 v[112:115], v[194:197], v[170:173], v[112:115]
	v_mfma_f32_16x16x32_bf16 v[116:119], v[204:207], v[170:173], v[116:119]
	v_mfma_f32_16x16x32_bf16 v[104:107], v[194:197], v[178:181], v[104:107]
	v_mfma_f32_16x16x32_bf16 v[108:111], v[204:207], v[178:181], v[108:111]
	v_mfma_f32_16x16x32_bf16 v[92:95], v[194:197], v[186:189], v[92:95]
	v_mfma_f32_16x16x32_bf16 v[100:103], v[204:207], v[186:189], v[100:103]
	v_mfma_f32_16x16x32_bf16 v[120:123], v[200:203], v[166:169], v[120:123]
	v_mfma_f32_16x16x32_bf16 v[124:127], v[208:211], v[166:169], v[124:127]
	v_mfma_f32_16x16x32_bf16 v[112:115], v[200:203], v[174:177], v[112:115]
	v_mfma_f32_16x16x32_bf16 v[116:119], v[208:211], v[174:177], v[116:119]
	v_mfma_f32_16x16x32_bf16 v[104:107], v[200:203], v[182:185], v[104:107]
	v_mfma_f32_16x16x32_bf16 v[108:111], v[208:211], v[182:185], v[108:111]
	v_mfma_f32_16x16x32_bf16 v[92:95], v[200:203], v[190:193], v[92:95]
	v_mfma_f32_16x16x32_bf16 v[100:103], v[208:211], v[190:193], v[100:103]
	s_setprio 0
	s_add_u32 s20, s20, 0x100
	s_addc_u32 s21, s21, 0
	s_add_u32 s81, s81, 0x100
	s_addc_u32 s82, s82, 0
	s_cmp_ge_u32 s83, s57
	s_mov_b32 s18, s83
	s_barrier
	s_cbranch_scc0 .LBB0_743
	s_branch .Lgemm_epi
.LBB0_743:
	ds_read_b128 v[138:141], v212
	ds_read_b128 v[150:153], v212 offset:1024
	ds_read_b128 v[154:157], v212 offset:2048
	ds_read_b128 v[158:161], v212 offset:3072
	s_add_i32 s83, s18, 2
	s_add_u32 s22, s20, 0x80
	s_addc_u32 s19, s21, 0
	s_cmp_eq_u32 s60, s18
	s_cselect_b32 s18, s8, s22
	s_cselect_b32 s19, s9, s19
	s_cselect_b32 s23, s17, s82
	s_cselect_b32 s22, s16, s81
	s_add_i32 m0, s49, 0xc000
	ds_read_b128 v[162:165], v148
	ds_read_b128 v[166:169], v148 offset:1024
	ds_read_b128 v[170:173], v148 offset:2048
	ds_read_b128 v[174:177], v148 offset:3072
	ds_read_b128 v[178:181], v148 offset:4096
	ds_read_b128 v[182:185], v148 offset:5120
	ds_read_b128 v[186:189], v148 offset:6144
	ds_read_b128 v[190:193], v148 offset:7168
	global_load_lds_dwordx4 v134, s[20:21]
	s_add_i32 m0, s49, 0xe000
	s_nop 0
	global_load_lds_dwordx4 v136, s[20:21]
	s_waitcnt lgkmcnt(8)
	s_barrier
	s_waitcnt lgkmcnt(0)
	s_setprio 1
	v_mfma_f32_16x16x32_bf16 v[24:27], v[138:141], v[162:165], v[24:27]
	v_mfma_f32_16x16x32_bf16 v[28:31], v[154:157], v[162:165], v[28:31]
	v_mfma_f32_16x16x32_bf16 v[16:19], v[138:141], v[170:173], v[16:19]
	v_mfma_f32_16x16x32_bf16 v[20:23], v[154:157], v[170:173], v[20:23]
	v_mfma_f32_16x16x32_bf16 v[8:11], v[138:141], v[178:181], v[8:11]
	v_mfma_f32_16x16x32_bf16 v[12:15], v[154:157], v[178:181], v[12:15]
	v_mfma_f32_16x16x32_bf16 v[0:3], v[138:141], v[186:189], v[0:3]
	v_mfma_f32_16x16x32_bf16 v[4:7], v[154:157], v[186:189], v[4:7]
	v_mfma_f32_16x16x32_bf16 v[24:27], v[150:153], v[166:169], v[24:27]
	v_mfma_f32_16x16x32_bf16 v[28:31], v[158:161], v[166:169], v[28:31]
	v_mfma_f32_16x16x32_bf16 v[16:19], v[150:153], v[174:177], v[16:19]
	v_mfma_f32_16x16x32_bf16 v[20:23], v[158:161], v[174:177], v[20:23]
	v_mfma_f32_16x16x32_bf16 v[8:11], v[150:153], v[182:185], v[8:11]
	v_mfma_f32_16x16x32_bf16 v[12:15], v[158:161], v[182:185], v[12:15]
	v_mfma_f32_16x16x32_bf16 v[0:3], v[150:153], v[190:193], v[0:3]
	v_mfma_f32_16x16x32_bf16 v[4:7], v[158:161], v[190:193], v[4:7]
	s_setprio 0
	s_barrier
	s_add_i32 s89, 0, 0x14000
	s_add_i32 vcc_lo, s26, s4
	s_mov_b32 m0, vcc_lo
	ds_read_b128 v[194:197], v213
	ds_read_b128 v[200:203], v213 offset:1024
	ds_read_b128 v[204:207], v213 offset:2048
	ds_read_b128 v[208:211], v213 offset:3072
	global_load_lds_dwordx4 v198, s[22:23]
	s_add_i32 m0, vcc_lo, 0x2000
	s_nop 0
	global_load_lds_dwordx4 v128, s[22:23]
	s_barrier
; #define PG8_STAGE(bufoff, gbase, voff) do { _Pragma("unroll") for (int _i = 0; _i < 2; ++_i) \
;         __builtin_amdgcn_global_load_lds((const unsigned*)((const char*)(gbase) + (voff)[_i]), (LAS unsigned*)(lds + (bufoff) + ldsw + _i * 8192), 16, 0, 0); } while (0)
; #define PG8_LDA(dst, b, h) do { _Pragma("unroll") for (int m = 0; m < 4; ++m) _Pragma("unroll") for (int k = 0; k < 2; ++k) dst[m][k] = *(const LAS bf16x8*)(lds + PG8_SA(b, h) + aoff + m * 2048 + k * 1024); } while (0)
; #define PG8_LDB(dst, b, h) do { _Pragma("unroll") for (int n = 0; n < 2; ++n) _Pragma("unroll") for (int k = 0; k < 2; ++k) dst[n][k] = *(const LAS bf16x8*)(lds + PG8_SB(b, h) + boff + n * 2048 + k * 1024); } while (0)
; #define PG8_MMA(ai, bj, At, Bt) do { __builtin_amdgcn_s_setprio(1); _Pragma("unroll") for (int m = 0; m < 4; ++m) _Pragma("unroll") for (int n = 0; n < 2; ++n) _Pragma("unroll") for (int k = 0; k < 2; ++k) \
;         acc[ai][bj][m][n] = __builtin_amdgcn_mfma_f32_16x16x32_bf16(Bt[n][k], At[m][k], acc[ai][bj][m][n], 0, 0, 0); __builtin_amdgcn_s_setprio(0); } while (0)
; #define PG8_WAIT_V(n) asm volatile("s_waitcnt vmcnt(" #n ")" ::: "memory")
; #define PG8_WAIT_L(n) asm volatile("s_waitcnt lgkmcnt(" #n ")" ::: "memory")
; #define PG8_BAR __builtin_amdgcn_s_barrier()
; #define PG8_SCHED __builtin_amdgcn_sched_barrier(0)
; template <class Epi>
; DI void gemm_phase(LAS unsigned char* lds, const Gemm g, const StaticOrder& S, const Epi& E, const int tid) {
;     ...
;             PG8_BAR; PG8_WAIT_L(0); PG8_MMA(0, 1, At, B1); PG8_BAR;
;             PG8_LDA(At, 0, 1); PG8_STAGE(PG8_SA(0, 0), a2, voffA);
;             PG8_BAR; PG8_WAIT_L(0); PG8_MMA(1, 0, At, B0); PG8_BAR; PG8_SCHED;
;             PG8_STAGE(PG8_SB(0, 1), b2 + hstep, voffB);
;             PG8_WAIT_V(6); PG8_BAR; PG8_MMA(1, 1, At, B1); PG8_BAR;
;             PG8_LDB(B0, 1, 0); PG8_SCHED; PG8_LDA(At, 1, 0); PG8_STAGE(PG8_SA(0, 1), a2 + hstep, voffA);
;             PG8_WAIT_L(8); PG8_BAR; PG8_WAIT_L(0); PG8_MMA(0, 0, At, B0); PG8_BAR; PG8_SCHED;
;             PG8_LDB(B1, 1, 1); PG8_STAGE(PG8_SB(1, 0), b3, voffB);
;             PG8_BAR; PG8_WAIT_L(0); PG8_MMA(0, 1, At, B1); PG8_BAR;
	s_waitcnt lgkmcnt(0)
	s_setprio 1
	v_mfma_f32_16x16x32_bf16 v[88:91], v[194:197], v[162:165], v[88:91]
	v_mfma_f32_16x16x32_bf16 v[96:99], v[204:207], v[162:165], v[96:99]
	v_mfma_f32_16x16x32_bf16 v[80:83], v[194:197], v[170:173], v[80:83]
	v_mfma_f32_16x16x32_bf16 v[84:87], v[204:207], v[170:173], v[84:87]
	v_mfma_f32_16x16x32_bf16 v[72:75], v[194:197], v[178:181], v[72:75]
	v_mfma_f32_16x16x32_bf16 v[76:79], v[204:207], v[178:181], v[76:79]
	v_mfma_f32_16x16x32_bf16 v[56:59], v[194:197], v[186:189], v[56:59]
	v_mfma_f32_16x16x32_bf16 v[64:67], v[204:207], v[186:189], v[64:67]
	v_mfma_f32_16x16x32_bf16 v[88:91], v[200:203], v[166:169], v[88:91]
	v_mfma_f32_16x16x32_bf16 v[96:99], v[208:211], v[166:169], v[96:99]
	v_mfma_f32_16x16x32_bf16 v[80:83], v[200:203], v[174:177], v[80:83]
	v_mfma_f32_16x16x32_bf16 v[84:87], v[208:211], v[174:177], v[84:87]
	v_mfma_f32_16x16x32_bf16 v[72:75], v[200:203], v[182:185], v[72:75]
	v_mfma_f32_16x16x32_bf16 v[76:79], v[208:211], v[182:185], v[76:79]
	v_mfma_f32_16x16x32_bf16 v[56:59], v[200:203], v[190:193], v[56:59]
	v_mfma_f32_16x16x32_bf16 v[64:67], v[208:211], v[190:193], v[64:67]
	s_setprio 0
	s_mov_b32 m0, s49
	s_barrier
	ds_read_b128 v[162:165], v148 offset:16384
	ds_read_b128 v[166:169], v148 offset:17408
	ds_read_b128 v[170:173], v148 offset:18432
	ds_read_b128 v[174:177], v148 offset:19456
	ds_read_b128 v[178:181], v148 offset:20480
	ds_read_b128 v[182:185], v148 offset:21504
	ds_read_b128 v[186:189], v148 offset:22528
	ds_read_b128 v[190:193], v148 offset:23552
	global_load_lds_dwordx4 v132, s[18:19]
	s_mov_b32 m0, s52
	s_nop 0
	global_load_lds_dwordx4 v130, s[18:19]
	s_barrier
	s_waitcnt lgkmcnt(0)
	s_setprio 1
	v_mfma_f32_16x16x32_bf16 v[60:63], v[138:141], v[162:165], v[60:63]
	v_mfma_f32_16x16x32_bf16 v[68:71], v[154:157], v[162:165], v[68:71]
	v_mfma_f32_16x16x32_bf16 v[48:51], v[138:141], v[170:173], v[48:51]
	v_mfma_f32_16x16x32_bf16 v[52:55], v[154:157], v[170:173], v[52:55]
	v_mfma_f32_16x16x32_bf16 v[40:43], v[138:141], v[178:181], v[40:43]
	v_mfma_f32_16x16x32_bf16 v[44:47], v[154:157], v[178:181], v[44:47]
	v_mfma_f32_16x16x32_bf16 v[32:35], v[138:141], v[186:189], v[32:35]
	v_mfma_f32_16x16x32_bf16 v[36:39], v[154:157], v[186:189], v[36:39]
	v_mfma_f32_16x16x32_bf16 v[60:63], v[150:153], v[166:169], v[60:63]
	v_mfma_f32_16x16x32_bf16 v[68:71], v[158:161], v[166:169], v[68:71]
	v_mfma_f32_16x16x32_bf16 v[48:51], v[150:153], v[174:177], v[48:51]
	v_mfma_f32_16x16x32_bf16 v[52:55], v[158:161], v[174:177], v[52:55]
	v_mfma_f32_16x16x32_bf16 v[40:43], v[150:153], v[182:185], v[40:43]
	v_mfma_f32_16x16x32_bf16 v[44:47], v[158:161], v[182:185], v[44:47]
	v_mfma_f32_16x16x32_bf16 v[32:35], v[150:153], v[190:193], v[32:35]
	v_mfma_f32_16x16x32_bf16 v[36:39], v[158:161], v[190:193], v[36:39]
	s_setprio 0
	s_barrier
	s_add_u32 s22, s22, s84
	s_addc_u32 s23, s23, 0
	s_add_i32 s89, s89, s4
	s_mov_b32 m0, s89
	s_nop 0
	global_load_lds_dwordx4 v198, s[22:23]
	s_add_i32 m0, s89, 0x2000
	s_nop 0
	global_load_lds_dwordx4 v128, s[22:23]
	s_waitcnt vmcnt(6)
	s_barrier
	s_setprio 1
	v_mfma_f32_16x16x32_bf16 v[120:123], v[194:197], v[162:165], v[120:123]
	v_mfma_f32_16x16x32_bf16 v[124:127], v[204:207], v[162:165], v[124:127]
	v_mfma_f32_16x16x32_bf16 v[112:115], v[194:197], v[170:173], v[112:115]
	v_mfma_f32_16x16x32_bf16 v[116:119], v[204:207], v[170:173], v[116:119]
	v_mfma_f32_16x16x32_bf16 v[104:107], v[194:197], v[178:181], v[104:107]
	v_mfma_f32_16x16x32_bf16 v[108:111], v[204:207], v[178:181], v[108:111]
	v_mfma_f32_16x16x32_bf16 v[92:95], v[194:197], v[186:189], v[92:95]
	v_mfma_f32_16x16x32_bf16 v[100:103], v[204:207], v[186:189], v[100:103]
	v_mfma_f32_16x16x32_bf16 v[120:123], v[200:203], v[166:169], v[120:123]
	v_mfma_f32_16x16x32_bf16 v[124:127], v[208:211], v[166:169], v[124:127]
	v_mfma_f32_16x16x32_bf16 v[112:115], v[200:203], v[174:177], v[112:115]
	v_mfma_f32_16x16x32_bf16 v[116:119], v[208:211], v[174:177], v[116:119]
	v_mfma_f32_16x16x32_bf16 v[104:107], v[200:203], v[182:185], v[104:107]
	v_mfma_f32_16x16x32_bf16 v[108:111], v[208:211], v[182:185], v[108:111]
	v_mfma_f32_16x16x32_bf16 v[92:95], v[200:203], v[190:193], v[92:95]
	v_mfma_f32_16x16x32_bf16 v[100:103], v[208:211], v[190:193], v[100:103]
	s_setprio 0
	s_add_i32 s22, 0, 0x18000
	s_barrier
	ds_read_b128 v[138:141], v214
	ds_read_b128 v[150:153], v214 offset:1024
	ds_read_b128 v[154:157], v214 offset:2048
	ds_read_b128 v[158:161], v214 offset:3072
	s_add_u32 s18, s18, s84
	s_addc_u32 s19, s19, 0
	s_mov_b32 m0, s53
	ds_read_b128 v[162:165], v148 offset:32768
	ds_read_b128 v[166:169], v148 offset:33792
	ds_read_b128 v[170:173], v148 offset:34816
	ds_read_b128 v[174:177], v148 offset:35840
	ds_read_b128 v[178:181], v148 offset:36864
	ds_read_b128 v[182:185], v148 offset:37888
	ds_read_b128 v[186:189], v148 offset:38912
	ds_read_b128 v[190:193], v148 offset:39936
	global_load_lds_dwordx4 v132, s[18:19]
	s_mov_b32 m0, s54
	s_nop 0
	global_load_lds_dwordx4 v130, s[18:19]
	s_waitcnt lgkmcnt(8)
	s_barrier
	s_waitcnt lgkmcnt(0)
	s_setprio 1
	v_mfma_f32_16x16x32_bf16 v[24:27], v[138:141], v[162:165], v[24:27]
	v_mfma_f32_16x16x32_bf16 v[28:31], v[154:157], v[162:165], v[28:31]
	v_mfma_f32_16x16x32_bf16 v[16:19], v[138:141], v[170:173], v[16:19]
	v_mfma_f32_16x16x32_bf16 v[20:23], v[154:157], v[170:173], v[20:23]
	v_mfma_f32_16x16x32_bf16 v[8:11], v[138:141], v[178:181], v[8:11]
	v_mfma_f32_16x16x32_bf16 v[12:15], v[154:157], v[178:181], v[12:15]
	v_mfma_f32_16x16x32_bf16 v[0:3], v[138:141], v[186:189], v[0:3]
	v_mfma_f32_16x16x32_bf16 v[4:7], v[154:157], v[186:189], v[4:7]
	v_mfma_f32_16x16x32_bf16 v[24:27], v[150:153], v[166:169], v[24:27]
	v_mfma_f32_16x16x32_bf16 v[28:31], v[158:161], v[166:169], v[28:31]
	v_mfma_f32_16x16x32_bf16 v[16:19], v[150:153], v[174:177], v[16:19]
	v_mfma_f32_16x16x32_bf16 v[20:23], v[158:161], v[174:177], v[20:23]
	v_mfma_f32_16x16x32_bf16 v[8:11], v[150:153], v[182:185], v[8:11]
	v_mfma_f32_16x16x32_bf16 v[12:15], v[158:161], v[182:185], v[12:15]
	v_mfma_f32_16x16x32_bf16 v[0:3], v[150:153], v[190:193], v[0:3]
	v_mfma_f32_16x16x32_bf16 v[4:7], v[158:161], v[190:193], v[4:7]
	s_setprio 0
	s_barrier
; #define PG8_STAGE(bufoff, gbase, voff) do { _Pragma("unroll") for (int _i = 0; _i < 2; ++_i) \
;         __builtin_amdgcn_global_load_lds((const unsigned*)((const char*)(gbase) + (voff)[_i]), (LAS unsigned*)(lds + (bufoff) + ldsw + _i * 8192), 16, 0, 0); } while (0)
; #define PG8_LDA(dst, b, h) do { _Pragma("unroll") for (int m = 0; m < 4; ++m) _Pragma("unroll") for (int k = 0; k < 2; ++k) dst[m][k] = *(const LAS bf16x8*)(lds + PG8_SA(b, h) + aoff + m * 2048 + k * 1024); } while (0)
; #define PG8_LDB(dst, b, h) do { _Pragma("unroll") for (int n = 0; n < 2; ++n) _Pragma("unroll") for (int k = 0; k < 2; ++k) dst[n][k] = *(const LAS bf16x8*)(lds + PG8_SB(b, h) + boff + n * 2048 + k * 1024); } while (0)
; #define PG8_MMA(ai, bj, At, Bt) do { __builtin_amdgcn_s_setprio(1); _Pragma("unroll") for (int m = 0; m < 4; ++m) _Pragma("unroll") for (int n = 0; n < 2; ++n) _Pragma("unroll") for (int k = 0; k < 2; ++k) \
;         acc[ai][bj][m][n] = __builtin_amdgcn_mfma_f32_16x16x32_bf16(Bt[n][k], At[m][k], acc[ai][bj][m][n], 0, 0, 0); __builtin_amdgcn_s_setprio(0); } while (0)
; #define PG8_WAIT_V(n) asm volatile("s_waitcnt vmcnt(" #n ")" ::: "memory")
; #define PG8_WAIT_L(n) asm volatile("s_waitcnt lgkmcnt(" #n ")" ::: "memory")
; #define PG8_BAR __builtin_amdgcn_s_barrier()
; #define PG8_SCHED __builtin_amdgcn_sched_barrier(0)
; template <class Epi>
; DI void gemm_phase(LAS unsigned char* lds, const Gemm g, const StaticOrder& S, const Epi& E, const int tid) {
;     ...
;             PG8_LDB(B1, 1, 1); PG8_STAGE(PG8_SB(1, 0), b3, voffB);
;             PG8_BAR; PG8_WAIT_L(0); PG8_MMA(0, 1, At, B1); PG8_BAR;
;             PG8_LDA(At, 1, 1); PG8_STAGE(PG8_SA(1, 0), a3, voffA);
;             PG8_BAR; PG8_WAIT_L(0); PG8_MMA(1, 0, At, B0); PG8_BAR; PG8_SCHED;
;             PG8_STAGE(PG8_SB(1, 1), b3 + hstep, voffB);
;             PG8_WAIT_V(6); PG8_BAR; PG8_MMA(1, 1, At, B1); PG8_BAR;
	s_add_i32 s18, 0, 0x1c000
	s_add_i32 s19, s22, s4
	s_mov_b32 m0, s19
	ds_read_b128 v[194:197], v215
	ds_read_b128 v[200:203], v215 offset:1024
	ds_read_b128 v[204:207], v215 offset:2048
	ds_read_b128 v[208:211], v215 offset:3072
	s_add_i32 vcc_hi, s60, 2
	s_cmp_eq_u32 vcc_hi, s83
	s_cselect_b32 s100, s16, s81
	s_cselect_b32 s101, s17, s82
	s_add_u32 s100, s100, 0x80
	s_addc_u32 s101, s101, 0
	global_load_lds_dwordx4 v198, s[100:101]
	s_add_i32 m0, s19, 0x2000
	s_nop 0
	global_load_lds_dwordx4 v128, s[100:101]
	s_barrier
	s_waitcnt lgkmcnt(0)
	s_setprio 1
	v_mfma_f32_16x16x32_bf16 v[88:91], v[194:197], v[162:165], v[88:91]
	v_mfma_f32_16x16x32_bf16 v[96:99], v[204:207], v[162:165], v[96:99]
	v_mfma_f32_16x16x32_bf16 v[80:83], v[194:197], v[170:173], v[80:83]
	v_mfma_f32_16x16x32_bf16 v[84:87], v[204:207], v[170:173], v[84:87]
	v_mfma_f32_16x16x32_bf16 v[72:75], v[194:197], v[178:181], v[72:75]
	v_mfma_f32_16x16x32_bf16 v[76:79], v[204:207], v[178:181], v[76:79]
	v_mfma_f32_16x16x32_bf16 v[56:59], v[194:197], v[186:189], v[56:59]
	v_mfma_f32_16x16x32_bf16 v[64:67], v[204:207], v[186:189], v[64:67]
	v_mfma_f32_16x16x32_bf16 v[88:91], v[200:203], v[166:169], v[88:91]
	v_mfma_f32_16x16x32_bf16 v[96:99], v[208:211], v[166:169], v[96:99]
	v_mfma_f32_16x16x32_bf16 v[80:83], v[200:203], v[174:177], v[80:83]
	v_mfma_f32_16x16x32_bf16 v[84:87], v[208:211], v[174:177], v[84:87]
	v_mfma_f32_16x16x32_bf16 v[72:75], v[200:203], v[182:185], v[72:75]
	v_mfma_f32_16x16x32_bf16 v[76:79], v[208:211], v[182:185], v[76:79]
	v_mfma_f32_16x16x32_bf16 v[56:59], v[200:203], v[190:193], v[56:59]
	v_mfma_f32_16x16x32_bf16 v[64:67], v[208:211], v[190:193], v[64:67]
	s_setprio 0
	s_mov_b32 m0, s55
	s_barrier
	ds_read_b128 v[162:165], v148 offset:49152
	ds_read_b128 v[166:169], v148 offset:50176
	ds_read_b128 v[170:173], v148 offset:51200
	ds_read_b128 v[174:177], v148 offset:52224
	ds_read_b128 v[178:181], v148 offset:53248
	ds_read_b128 v[182:185], v148 offset:54272
	ds_read_b128 v[186:189], v148 offset:55296
	ds_read_b128 v[190:193], v148 offset:56320
	s_add_u32 s100, s20, 0x80
	s_addc_u32 s101, s21, 0
	s_add_i32 vcc_hi, s60, 2
	s_cmp_eq_u32 vcc_hi, s83
	s_cselect_b32 s100, s8, s100
	s_cselect_b32 s101, s9, s101
	s_add_u32 s100, s100, 0x80
	s_addc_u32 s101, s101, 0
	global_load_lds_dwordx4 v132, s[100:101]
	s_mov_b32 m0, s56
	s_nop 0
	global_load_lds_dwordx4 v130, s[100:101]
	s_barrier
	s_waitcnt lgkmcnt(0)
	s_setprio 1
	v_mfma_f32_16x16x32_bf16 v[60:63], v[138:141], v[162:165], v[60:63]
	v_mfma_f32_16x16x32_bf16 v[68:71], v[154:157], v[162:165], v[68:71]
	v_mfma_f32_16x16x32_bf16 v[48:51], v[138:141], v[170:173], v[48:51]
	v_mfma_f32_16x16x32_bf16 v[52:55], v[154:157], v[170:173], v[52:55]
	v_mfma_f32_16x16x32_bf16 v[40:43], v[138:141], v[178:181], v[40:43]
	v_mfma_f32_16x16x32_bf16 v[44:47], v[154:157], v[178:181], v[44:47]
	v_mfma_f32_16x16x32_bf16 v[32:35], v[138:141], v[186:189], v[32:35]
	v_mfma_f32_16x16x32_bf16 v[36:39], v[154:157], v[186:189], v[36:39]
	v_mfma_f32_16x16x32_bf16 v[60:63], v[150:153], v[166:169], v[60:63]
	v_mfma_f32_16x16x32_bf16 v[68:71], v[158:161], v[166:169], v[68:71]
	v_mfma_f32_16x16x32_bf16 v[48:51], v[150:153], v[174:177], v[48:51]
	v_mfma_f32_16x16x32_bf16 v[52:55], v[158:161], v[174:177], v[52:55]
	v_mfma_f32_16x16x32_bf16 v[40:43], v[150:153], v[182:185], v[40:43]
	v_mfma_f32_16x16x32_bf16 v[44:47], v[158:161], v[182:185], v[44:47]
	v_mfma_f32_16x16x32_bf16 v[32:35], v[150:153], v[190:193], v[32:35]
	v_mfma_f32_16x16x32_bf16 v[36:39], v[158:161], v[190:193], v[36:39]
	s_setprio 0
	s_barrier
	s_add_i32 s18, s18, s4
	s_add_i32 vcc_hi, s60, 2
	s_cmp_eq_u32 vcc_hi, s83
	s_cselect_b32 s100, s16, s81
	s_cselect_b32 s101, s17, s82
	s_add_u32 s100, s100, s84
	s_addc_u32 s101, s101, 0
	s_add_u32 s100, s100, 0x80
	s_addc_u32 s101, s101, 0
	s_mov_b32 m0, s18
	s_nop 0
	global_load_lds_dwordx4 v198, s[100:101]
	s_add_i32 m0, s18, 0x2000
	s_nop 0
	global_load_lds_dwordx4 v128, s[100:101]
	s_waitcnt vmcnt(6)
	s_barrier
	s_setprio 1
	v_mfma_f32_16x16x32_bf16 v[120:123], v[194:197], v[162:165], v[120:123]
	v_mfma_f32_16x16x32_bf16 v[124:127], v[204:207], v[162:165], v[124:127]
	v_mfma_f32_16x16x32_bf16 v[112:115], v[194:197], v[170:173], v[112:115]
	v_mfma_f32_16x16x32_bf16 v[116:119], v[204:207], v[170:173], v[116:119]
	v_mfma_f32_16x16x32_bf16 v[104:107], v[194:197], v[178:181], v[104:107]
	v_mfma_f32_16x16x32_bf16 v[108:111], v[204:207], v[178:181], v[108:111]
	v_mfma_f32_16x16x32_bf16 v[92:95], v[194:197], v[186:189], v[92:95]
	v_mfma_f32_16x16x32_bf16 v[100:103], v[204:207], v[186:189], v[100:103]
	v_mfma_f32_16x16x32_bf16 v[120:123], v[200:203], v[166:169], v[120:123]
	v_mfma_f32_16x16x32_bf16 v[124:127], v[208:211], v[166:169], v[124:127]
	v_mfma_f32_16x16x32_bf16 v[112:115], v[200:203], v[174:177], v[112:115]
	v_mfma_f32_16x16x32_bf16 v[116:119], v[208:211], v[174:177], v[116:119]
	v_mfma_f32_16x16x32_bf16 v[104:107], v[200:203], v[182:185], v[104:107]
	v_mfma_f32_16x16x32_bf16 v[108:111], v[208:211], v[182:185], v[108:111]
	v_mfma_f32_16x16x32_bf16 v[92:95], v[200:203], v[190:193], v[92:95]
	v_mfma_f32_16x16x32_bf16 v[100:103], v[208:211], v[190:193], v[100:103]
	s_setprio 0
	s_add_u32 s20, s20, 0x100
	s_addc_u32 s21, s21, 0
	s_add_u32 s81, s81, 0x100
	s_addc_u32 s82, s82, 0
	s_cmp_ge_u32 s83, s57
	s_mov_b32 s18, s83
	s_barrier
	s_cbranch_scc0 .LBB0_743
